# workgroup stagger (half the workgroups enter P1/P5 2us late) so store-bound tile epilogues stop hitting memory in lockstep
# baseline (speedup 1.0000x reference)
; #define LAS __attribute__((address_space(3)))
; template <class Epi>
; __device__ __forceinline__ void gemm_phase(LAS unsigned char* lds, const Gemm g, const StaticOrder& S, const Epi& E) {
;     int tid = threadIdx.x;
;     asm volatile("" : "+v"(tid));
;     const int wid = __builtin_amdgcn_readfirstlane(tid >> 6), lane = tid & 63, wr = wid >> 2, wc = wid & 3, fr = lane & 15, fq = lane >> 4;
;     const int K = g.K, nt = K / BK;
;     unsigned voffA[2], voffB[2];
; #pragma unroll
;     for (int i = 0; i < 2; ++i) { int R, C; stage_rc(tid * 16 + i * 8192, R, C); const int Rb = (R & ~31) + perm32(R & 31);
;         voffA[i] = (unsigned)(R * K + C) * 2u; voffB[i] = (unsigned)(Rb * K + C) * 2u; }
;     const size_t kstep = (size_t)(BK * 2);
;     const size_t hstep = (size_t)HALF * K * 2;
;     const size_t tstep = 2 * hstep;
;     const unsigned ldsw = (unsigned)wid * 1024u;
;     const int aoff = lds_byte(wr * 64 + fr, fq * 8), boff = lds_byte(wc * 32 + fr, fq * 8);
;     ...
;     Unit cur, nxt; int ui = 0;
;     if (!S.next(0, cur)) return;
;     f32x4 acc[2][2][4][2];
; #pragma unroll
;     for (int a = 0; a < 2; ++a)
; #pragma unroll
;         for (int b = 0; b < 2; ++b)
; #pragma unroll
;             for (int m = 0; m < 4; ++m)
; #pragma unroll
;                 for (int n = 0; n < 2; ++n) acc[a][b][m][n] = (f32x4){0.f, 0.f, 0.f, 0.f};
;     h16x8 At[4][2], B0[2][2], B1[2][2];
;     const char* cA = (const char*)g.A + (size_t)cur.pm * tstep; const char* cB = (const char*)g.Bt + (size_t)cur.pn * tstep;
;     PG8_STAGE(PG8_SB(0, 0), cB, voffB); PG8_STAGE(PG8_SA(0, 0), cA, voffA); PG8_STAGE(PG8_SB(0, 1), cB + hstep, voffB); PG8_STAGE(PG8_SA(0, 1), cA + hstep, voffA);
;     if (wr == 1) PG8_BAR;
;     PG8_WAIT_V(4); PG8_BAR;
; __global__ void __launch_bounds__(512, 2) hymba_fwd(Params p) {
;     ...
;         LAS unsigned* hist = (LAS unsigned*)lds;
;         if (threadIdx.x < 16) hist[threadIdx.x] = 0u;
;         __syncthreads();
;         for (int i = threadIdx.x; i < G; i += 512) atomicAdd((unsigned*)(hist + (xb_ld(&xb.bar[3200 + i]) & 15u)), 1u);
;         __syncthreads();
;         unsigned cnt = 0u;
; #pragma unroll
;         for (unsigned j = 0; j < 16; ++j) cnt += (hist[j] > 0u) ? 1u : 0u;
;         const unsigned mine = hist[xb.x];
;         xb.nloc = mine > 0u ? mine : 1u; xb.nx = cnt > 0u ? cnt : 1u;
;         __syncthreads();
.LBB0_77:
	s_or_b64 exec, exec, s[0:1]
	v_mov_b32_e32 v129, 0
	s_waitcnt lgkmcnt(0)
	s_barrier
	ds_read_b128 v[0:3], v129
	ds_read_b128 v[4:7], v129 offset:16
	ds_read_b128 v[8:11], v129 offset:32
	ds_read_b128 v[12:15], v129 offset:48
	s_lshl_b32 s0, s89, 2
	s_waitcnt lgkmcnt(3)
	v_cmp_ne_u32_e32 vcc, 0, v1
	s_add_i32 s0, s0, 0
	v_mov_b32_e32 v16, s0
	v_cndmask_b32_e64 v1, 0, 1, vcc
	v_cmp_ne_u32_e32 vcc, 0, v0
	ds_read_b32 v16, v16
	s_add_u32 s86, s82, 0x1b72900
	v_addc_co_u32_e32 v0, vcc, 0, v1, vcc
	v_cmp_ne_u32_e32 vcc, 0, v2
	s_addc_u32 s87, s83, 0
	s_add_u32 s90, s82, 0x8620000
	v_cndmask_b32_e64 v1, 0, 1, vcc
	v_cmp_ne_u32_e32 vcc, 0, v3
	s_addc_u32 s91, s83, 0
	s_waitcnt lgkmcnt(1)
	v_cmp_ne_u32_e64 s[6:7], 0, v15
	v_addc_co_u32_e32 v0, vcc, v0, v1, vcc
	v_cmp_ne_u32_e32 vcc, 0, v4
	s_waitcnt lgkmcnt(0)
	v_readfirstlane_b32 s3, v16
	v_cndmask_b32_e64 v1, 0, 1, vcc
	v_cmp_ne_u32_e32 vcc, 0, v5
	s_barrier
	s_bitcmp1_b32 s2, 3
	s_cbranch_scc0 .Lstag1
	s_sleep 64
.Lstag1:
	s_nop 0
	v_addc_co_u32_e32 v0, vcc, v0, v1, vcc
	v_cmp_ne_u32_e32 vcc, 0, v6
	s_cmpk_lt_i32 s2, 0x3cf
	s_nop 0
	v_cndmask_b32_e64 v1, 0, 1, vcc
	v_cmp_ne_u32_e32 vcc, 0, v7
	s_nop 1
	v_addc_co_u32_e32 v0, vcc, v0, v1, vcc
	v_cmp_ne_u32_e32 vcc, 0, v8
	s_nop 1
	v_cndmask_b32_e64 v1, 0, 1, vcc
	v_cmp_ne_u32_e32 vcc, 0, v9
	v_mov_b32_e32 v9, v132
	s_nop 0
	v_addc_co_u32_e32 v0, vcc, v0, v1, vcc
	v_cmp_ne_u32_e32 vcc, 0, v10
	v_readfirstlane_b32 s44, v9
	s_nop 0
	v_cndmask_b32_e64 v1, 0, 1, vcc
	v_cmp_ne_u32_e32 vcc, 0, v11
	s_nop 1
	v_addc_co_u32_e32 v0, vcc, v0, v1, vcc
	v_cmp_ne_u32_e32 vcc, 0, v12
	s_nop 1
	v_cndmask_b32_e64 v1, 0, 1, vcc
	v_cmp_ne_u32_e32 vcc, 0, v13
	s_nop 1
	v_addc_co_u32_e32 v131, vcc, v0, v1, vcc
	v_cmp_ne_u32_e32 vcc, 0, v14
	s_nop 1
	v_cndmask_b32_e64 v133, 0, 1, vcc
	s_cbranch_scc0 .LBB0_89
	v_lshlrev_b32_e32 v0, 4, v9
	v_add_u32_e32 v1, 0x2000, v0
	v_ashrrev_i32_e32 v2, 31, v1
	v_lshrrev_b32_e32 v2, 22, v2
	v_add_u32_e32 v2, v1, v2
	v_ashrrev_i32_e32 v8, 10, v2
	v_mul_i32_i24_e32 v2, 0x400, v8
	v_sub_u32_e32 v1, v1, v2
	v_lshrrev_b32_e32 v2, 4, v1
	v_bitop3_b32 v1, v2, v1, 32 bitop3:0x6c
	v_ashrrev_i32_e32 v2, 31, v1
	v_lshrrev_b32_e32 v2, 26, v2
	v_add_u32_e32 v2, v1, v2
	v_lshlrev_b32_e32 v3, 3, v8
	v_ashrrev_i32_e32 v10, 6, v2
	v_and_b32_e32 v3, -16, v3
	v_add_u32_e32 v3, v10, v3
	v_and_b32_e32 v4, 3, v10
	s_mov_b32 s1, 0x1fffe0
	v_lshrrev_b32_e32 v5, 2, v3
	v_lshlrev_b32_e32 v6, 1, v3
	v_and_b32_e32 v2, 0xc0, v2
	v_and_or_b32 v4, v3, s1, v4
	v_and_b32_e32 v5, 4, v5
	v_and_b32_e32 v6, 24, v6
	v_sub_u32_e32 v1, v1, v2
	v_mov_b32_e32 v2, 1
	v_or3_b32 v4, v4, v5, v6
	v_lshlrev_b32_e32 v5, 5, v8
	v_ashrrev_i16_sdwa v1, v2, sext(v1) dst_sel:DWORD dst_unused:UNUSED_PAD src0_sel:DWORD src1_sel:BYTE_0
	v_and_b32_e32 v5, 32, v5
	v_bfe_i32 v11, v1, 0, 16
	v_add_lshl_u32 v1, v5, v11, 1
	v_lshl_add_u32 v138, v4, 11, v1
	v_lshl_add_u32 v140, v3, 11, v1
	v_bfe_i32 v1, v9, 27, 1
	v_lshrrev_b32_e32 v1, 22, v1
	v_add_u32_e32 v1, v0, v1
	v_and_b32_e32 v1, 0xfffffc00, v1
	v_sub_u32_e32 v0, v0, v1
	v_lshrrev_b32_e32 v1, 4, v0
	v_ashrrev_i32_e32 v3, 31, v9
	v_bitop3_b32 v0, v1, v0, 32 bitop3:0x6c
	v_lshrrev_b32_e32 v3, 26, v3
	v_ashrrev_i32_e32 v1, 31, v0
	v_add_u32_e32 v3, v9, v3
	v_lshrrev_b32_e32 v1, 26, v1
	v_ashrrev_i32_e32 v13, 6, v3
	v_add_u32_e32 v1, v0, v1
	v_lshlrev_b32_e32 v3, 3, v13
	v_ashrrev_i32_e32 v12, 6, v1
	v_and_b32_e32 v3, -16, v3
	v_add_u32_e32 v3, v12, v3
	v_and_b32_e32 v4, 3, v12
	s_ashr_i32 s52, s2, 31
	v_and_or_b32 v4, v3, s1, v4
	s_lshr_b32 s1, s52, 29
	s_add_i32 s1, s2, s1
	s_ashr_i32 s1, s1, 3
	s_mul_i32 s8, s2, 0x7a
	s_mulk_i32 s1, 0xfc31
	s_add_i32 s1, s1, s8
	s_mul_hi_i32 s8, s1, 0x88888889
	s_add_i32 s8, s8, s1
	s_lshr_b32 s10, s8, 31
	s_ashr_i32 s8, s8, 6
	v_lshrrev_b32_e32 v5, 2, v3
	v_lshlrev_b32_e32 v6, 1, v3
	v_and_b32_e32 v1, 0xc0, v1
	s_add_i32 s8, s8, s10
	v_and_b32_e32 v5, 4, v5
	v_and_b32_e32 v6, 24, v6
	v_sub_u32_e32 v0, v0, v1
	s_lshl_b32 s24, s8, 3
	v_or3_b32 v4, v4, v5, v6
	v_lshlrev_b32_e32 v5, 5, v13
	v_ashrrev_i16_sdwa v0, v2, sext(v0) dst_sel:DWORD dst_unused:UNUSED_PAD src0_sel:DWORD src1_sel:BYTE_0
	s_sub_i32 s10, 0x41, s24
	s_mulk_i32 s8, 0x78
	v_and_b32_e32 v5, 32, v5
	v_bfe_i32 v14, v0, 0, 16
	s_min_u32 s25, s10, 8
	s_sub_i32 s1, s1, s8
	v_add_lshl_u32 v0, v5, v14, 1
	s_sext_i32_i8 s8, s1
	v_cvt_f32_ubyte0_e32 v2, s25
	v_lshl_add_u32 v128, v4, 11, v0
	v_cvt_f32_i32_e32 v1, s8
	v_rcp_iflag_f32_e32 v4, v2
	v_lshl_add_u32 v144, v3, 11, v0
	s_ashr_i32 s0, s44, 6
	s_ashr_i32 s8, s8, 30
	v_mul_f32_e32 v0, v1, v4
	v_trunc_f32_e32 v0, v0
	v_fma_f32 v1, -v0, v2, v1
	v_cvt_i32_f32_e32 v0, v0
	s_ashr_i32 s9, s44, 8
	s_lshl_b32 s45, s0, 10
	s_or_b32 s8, s8, 1
	v_cmp_ge_f32_e64 s[10:11], |v1|, v2
	s_and_b64 s[10:11], s[10:11], exec
	s_cselect_b32 s8, s8, 0
	v_readfirstlane_b32 s10, v0
	s_add_i32 s8, s10, s8
	s_mul_i32 s10, s8, s25
	s_sub_i32 s1, s1, s10
	s_sext_i32_i8 s1, s1
	s_add_i32 s10, s24, s1
	s_ashr_i32 s11, s10, 31
	s_bfe_i64 s[26:27], s[8:9], 0x80000
	s_lshl_b64 s[24:25], s[10:11], 19
	s_lshl_b64 s[26:27], s[26:27], 19
	s_add_u32 s38, s82, s26
	s_addc_u32 s39, s83, s27
	s_add_i32 s11, s45, 0
	s_add_i32 m0, s11, 0x10000
	v_mov_b32_e32 v139, v129
	global_load_lds_dwordx4 v128, s[38:39]
	s_add_i32 m0, s11, 0x12000
	s_add_u32 s34, s86, s24
	global_load_lds_dwordx4 v138, s[38:39]
	s_addc_u32 s35, s87, s25
	s_mov_b32 m0, s11
	s_add_i32 s53, s11, 0x2000
	global_load_lds_dwordx4 v144, s[34:35]
	s_mov_b32 m0, s53
	s_add_u32 s24, s38, 0x40000
	global_load_lds_dwordx4 v140, s[34:35]
	s_addc_u32 s25, s39, 0
	s_add_i32 m0, s11, 0x14000
	v_mov_b32_e32 v145, v129
	global_load_lds_dwordx4 v128, s[24:25]
	s_add_i32 m0, s11, 0x16000
	v_mov_b32_e32 v141, v129
	global_load_lds_dwordx4 v138, s[24:25]
	s_add_u32 s24, s34, 0x40000
	s_addc_u32 s25, s35, 0
	s_add_i32 s54, s11, 0x4000
	s_mov_b32 m0, s54
	s_add_i32 s55, s11, 0x6000
	global_load_lds_dwordx4 v144, s[24:25]
	s_mov_b32 m0, s55
	v_lshl_add_u64 v[6:7], s[38:39], 0, v[128:129]
	global_load_lds_dwordx4 v140, s[24:25]
	v_lshl_add_u64 v[4:5], s[38:39], 0, v[138:139]
	v_lshl_add_u64 v[2:3], s[34:35], 0, v[144:145]
	s_cmp_lg_u32 s9, 1
	v_lshl_add_u64 v[0:1], s[34:35], 0, v[140:141]
	s_cbranch_scc1 .LBB0_80
	s_barrier

;     __device__ bool next(int i, Unit& u) const {
;         const long L = (long)i * G + c; if (L >= nwg) return false;
;         int wgid = (int)L; { const int q = nwg / NXCD, r = nwg % NXCD, xcd = wgid % NXCD, off = wgid / NXCD; wgid = (xcd < r ? xcd * (q + 1) : r * (q + 1) + (xcd - r) * q) + off; }
;         const int nig = WGM * nN, gid = wgid / nig, fm = gid * WGM, gsz = (nM - fm) < WGM ? (nM - fm) : WGM;
;         u.pm = fm + ((wgid % nig) % gsz); u.pn = (wgid % nig) / gsz; return true;
; __global__ void __launch_bounds__(512, 2) hymba_fwd(Params p) {
;     ...
;     {
;         pg8::Gemm g{(const h16*)(ws + OFF_X116), (const h16*)(ws + OFF_WT_UP), MP, DFF, D};
;         pg8::StaticOrder S; S.init(MP, DFF, G, c);
;         Epi<2> E{(h16*)(ws + OFF_HID16), DFF, nullptr, 0, nullptr, 0, (float*)(ws + OFF_SS1), nullptr};
;         pg8::gemm_phase(lds, g, S, E);
.LBB0_468:
	s_or_b64 exec, exec, s[0:1]
	s_add_u32 s12, s82, 0x7cf2900
	s_addc_u32 s13, s83, 0
	v_mov_b32_e32 v8, v132
	s_barrier
	s_bitcmp1_b32 s2, 3
	s_cbranch_scc0 .Lstag5
	s_sleep 64
.Lstag5:
	s_cmpk_gt_i32 s2, 0x3ff
	v_readfirstlane_b32 s41, v8
	s_cbranch_scc1 .LBB0_488
	s_lshr_b32 s0, s3, 29
	s_add_i32 s6, s2, s0
	s_and_b32 s0, s6, -8
	s_sub_i32 s8, s2, s0
	s_cmp_gt_i32 s8, -1
	s_cbranch_scc0 .LBB0_471
	s_lshl_b32 s7, s8, 7
	s_cbranch_execz .LBB0_472
	s_branch .LBB0_473
